# attention bias-table fill: straight-line batched loads instead of load-wait loop
# baseline (speedup 1.0000x reference)
; __device__ __forceinline__ void phase_attn(const Ctx& C, const float* relb  , int layer) {
;     ...
;     for (int i = tid; i < 8 * 257; i += 512) tbl[i] = relb[i] * LOG2E;
;     __syncthreads();
.LBB0_247:
	s_or_b64 exec, exec, s[4:5]
	v_readlane_b32 s36, v255, 10
	v_mov_b32_e32 v4, v162
	s_waitcnt lgkmcnt(0)
	v_mov_b32_e32 v0, v163
	v_readlane_b32 s50, v255, 24
	v_readlane_b32 s51, v255, 25
	s_movk_i32 s2, 0x808
	s_mov_b32 s69, s11
	s_barrier
	s_mov_b64 s[12:13], s[50:51]
	v_cmp_gt_i32_e32 vcc, s2, v0
	v_readlane_b32 s37, v255, 11
	v_readlane_b32 s38, v255, 12
	v_readlane_b32 s39, v255, 13
	v_readlane_b32 s40, v255, 14
	v_readlane_b32 s41, v255, 15
	v_readlane_b32 s42, v255, 16
	v_readlane_b32 s43, v255, 17
	v_readlane_b32 s44, v255, 18
	v_readlane_b32 s45, v255, 19
	v_readlane_b32 s46, v255, 20
	v_readlane_b32 s47, v255, 21
	v_readlane_b32 s48, v255, 22
	v_readlane_b32 s49, v255, 23
	s_and_saveexec_b64 s[4:5], vcc
	s_cbranch_execz .LBB0_260
	v_readlane_b32 s20, v254, 14
	v_readlane_b32 s21, v254, 15
	v_readlane_b32 s3, v255, 30
	s_mul_i32 s2, s68, 0x2020
	s_add_u32 s20, s20, s2
	s_addc_u32 s21, s21, 0
	s_nop 3
	v_lshlrev_b32_e32 v1, 2, v0
	global_load_dword v2, v1, s[20:21]
	global_load_dword v3, v1, s[20:21] offset:2048
	v_add_u32_e32 v5, 0x1000, v1
	global_load_dword v6, v5, s[20:21]
	global_load_dword v7, v5, s[20:21] offset:2048
	v_add_u32_e32 v8, 0x2000, v1
	v_add_u32_e32 v10, s3, v1
	v_mov_b32_e32 v11, 0x3fb8aa3b
	v_cmp_gt_u32_e32 vcc, 8, v0
	s_and_saveexec_b64 s[14:15], vcc
	global_load_dword v9, v8, s[20:21]
	s_or_b64 exec, exec, s[14:15]
	s_waitcnt vmcnt(0)
	v_mul_f32_e32 v2, v11, v2
	v_mul_f32_e32 v3, v11, v3
	v_mul_f32_e32 v6, v11, v6
	v_mul_f32_e32 v7, v11, v7
	ds_write_b32 v10, v2
	ds_write_b32 v10, v3 offset:2048
	ds_write_b32 v10, v6 offset:4096
	ds_write_b32 v10, v7 offset:6144
	s_and_saveexec_b64 s[14:15], vcc
	s_waitcnt vmcnt(0)
	v_mul_f32_e32 v9, v11, v9
	ds_write_b32 v10, v9 offset:8192
	s_or_b64 exec, exec, s[14:15]
